# GATE-AHEAD: attention epilogue - all seven gate-row loads issued up front into free registers, copied at first use, vmcnt re-derived, output stores never waited for (on EPI-PIPE2)
# baseline (speedup 1.0000x reference)
.LBB0_991:
	s_waitcnt vmcnt(0) lgkmcnt(0)
	s_barrier
	s_andn2_b64 vcc, exec, s[4:5]
	s_cbranch_vccnz .LBB0_972
	v_lshlrev_b64 v[66:67], 12, v[142:143]
	v_lshl_add_u64 v[66:67], s[10:11], 0, v[66:67]
	s_lshl_b32 s6, s26, 1
	v_lshl_add_u64 v[66:67], v[66:67], 0, s[6:7]
	v_mov_b32_e32 v141, v131
	v_lshl_add_u64 v[78:79], v[66:67], 0, v[140:141]
	v_add_co_u32_e32 v84, vcc, s37, v78
	s_nop 1
	v_mov_b32_e32 v110, v14
	v_addc_co_u32_e32 v85, vcc, 0, v79, vcc
	global_load_dwordx4 v[66:69], v[84:85], off offset:2048
	ds_read2st64_b32 v[80:81], v70 offset1:1
	ds_read2st64_b32 v[124:125], v70 offset0:2 offset1:3
	ds_read2st64_b32 v[142:143], v70 offset0:4 offset1:5
	ds_read2st64_b32 v[106:107], v70 offset0:6 offset1:7
	ds_read2st64_b32 v[104:105], v70 offset0:8 offset1:9
	ds_read2st64_b32 v[102:103], v70 offset0:10 offset1:11
	ds_read2st64_b32 v[100:101], v70 offset0:12 offset1:13
	ds_read2st64_b32 v[98:99], v70 offset0:14 offset1:15
	ds_read2st64_b32 v[96:97], v70 offset0:16 offset1:17
	ds_read2st64_b32 v[94:95], v70 offset0:18 offset1:19
	ds_read2st64_b32 v[92:93], v70 offset0:20 offset1:21
	ds_read2st64_b32 v[90:91], v70 offset0:22 offset1:23
	ds_read2st64_b32 v[88:89], v70 offset0:24 offset1:25
	ds_read2st64_b32 v[86:87], v70 offset0:26 offset1:27
	ds_read2st64_b32 v[112:113], v70 offset0:28 offset1:29
	ds_read2st64_b32 v[116:117], v70 offset0:30 offset1:31
	ds_read_b128 v[74:77], v193
	ds_read_b128 v[70:73], v193 offset:32
	v_mov_b32_e32 v111, v16
	v_mov_b32_e32 v16, v15
	s_waitcnt lgkmcnt(3)
	v_cvt_f32_f16_e32 v15, v113
	v_cvt_f32_f16_e32 v14, v112
	v_cvt_f32_f16_sdwa v113, v113 dst_sel:DWORD dst_unused:UNUSED_PAD src0_sel:WORD_1
	v_cvt_f32_f16_sdwa v112, v112 dst_sel:DWORD dst_unused:UNUSED_PAD src0_sel:WORD_1
	s_waitcnt lgkmcnt(2)
	v_cvt_f32_f16_e32 v115, v117
	v_cvt_f32_f16_e32 v114, v116
	v_cvt_f32_f16_sdwa v117, v117 dst_sel:DWORD dst_unused:UNUSED_PAD src0_sel:WORD_1
	v_cvt_f32_f16_sdwa v116, v116 dst_sel:DWORD dst_unused:UNUSED_PAD src0_sel:WORD_1
	v_cvt_f32_f16_sdwa v123, v80 dst_sel:DWORD dst_unused:UNUSED_PAD src0_sel:WORD_1
	v_cvt_f32_f16_e32 v122, v80
	v_cvt_f32_f16_sdwa v127, v143 dst_sel:DWORD dst_unused:UNUSED_PAD src0_sel:WORD_1
	v_cvt_f32_f16_e32 v126, v143
	v_cvt_f32_f16_sdwa v143, v142 dst_sel:DWORD dst_unused:UNUSED_PAD src0_sel:WORD_1
	v_cvt_f32_f16_e32 v142, v142
	v_mov_b32_e32 v108, v10
	v_mov_b32_e32 v109, v12
	v_mov_b32_e32 v12, v11
	v_pk_fma_f32 v[144:145], v[108:109], v[82:83], v[14:15] op_sel_hi:[1,0,1] neg_lo:[0,0,1] neg_hi:[0,0,1]
	v_pk_fma_f32 v[14:15], v[12:13], v[82:83], v[112:113] op_sel_hi:[1,0,1] neg_lo:[0,0,1] neg_hi:[0,0,1]
	v_pk_fma_f32 v[12:13], v[16:17], v[82:83], v[116:117] op_sel_hi:[1,0,1] neg_lo:[0,0,1] neg_hi:[0,0,1]
	v_pk_mul_f32 v[16:17], v[14:15], v[14:15]
	v_pk_fma_f32 v[108:109], v[110:111], v[82:83], v[114:115] op_sel_hi:[1,0,1] neg_lo:[0,0,1] neg_hi:[0,0,1]
	v_pk_fma_f32 v[114:115], v[50:51], v[82:83], v[122:123] op_sel_hi:[1,0,1] neg_lo:[0,0,1] neg_hi:[0,0,1]
	v_pk_fma_f32 v[122:123], v[58:59], v[82:83], v[142:143] op_sel_hi:[1,0,1] neg_lo:[0,0,1] neg_hi:[0,0,1]
	v_pk_fma_f32 v[142:143], v[144:145], v[144:145], v[16:17]
	v_cvt_f32_f16_sdwa v17, v106 dst_sel:DWORD dst_unused:UNUSED_PAD src0_sel:WORD_1
	v_cvt_f32_f16_e32 v16, v106
	v_cvt_f32_f16_sdwa v119, v81 dst_sel:DWORD dst_unused:UNUSED_PAD src0_sel:WORD_1
	v_cvt_f32_f16_e32 v118, v81
	v_pk_mul_f32 v[50:51], v[12:13], v[12:13]
	v_pk_fma_f32 v[160:161], v[62:63], v[82:83], v[16:17] op_sel_hi:[1,0,1] neg_lo:[0,0,1] neg_hi:[0,0,1]
	v_cvt_f32_f16_sdwa v17, v103 dst_sel:DWORD dst_unused:UNUSED_PAD src0_sel:WORD_1
	v_cvt_f32_f16_e32 v16, v103
	v_pk_fma_f32 v[146:147], v[108:109], v[108:109], v[50:51]
	v_cvt_f32_f16_sdwa v51, v105 dst_sel:DWORD dst_unused:UNUSED_PAD src0_sel:WORD_1
	v_cvt_f32_f16_e32 v50, v105
	v_cvt_f32_f16_sdwa v121, v125 dst_sel:DWORD dst_unused:UNUSED_PAD src0_sel:WORD_1
	v_cvt_f32_f16_e32 v120, v125
	v_pk_fma_f32 v[110:111], v[52:53], v[82:83], v[118:119] op_sel_hi:[1,0,1] neg_lo:[0,0,1] neg_hi:[0,0,1]
	v_pk_fma_f32 v[52:53], v[40:41], v[82:83], v[16:17] op_sel_hi:[1,0,1] neg_lo:[0,0,1] neg_hi:[0,0,1]
	v_cvt_f32_f16_sdwa v17, v102 dst_sel:DWORD dst_unused:UNUSED_PAD src0_sel:WORD_1
	v_cvt_f32_f16_e32 v16, v102
	v_cvt_f32_f16_sdwa v125, v124 dst_sel:DWORD dst_unused:UNUSED_PAD src0_sel:WORD_1
	v_cvt_f32_f16_e32 v124, v124
	v_pk_fma_f32 v[50:51], v[36:37], v[82:83], v[50:51] op_sel_hi:[1,0,1] neg_lo:[0,0,1] neg_hi:[0,0,1]
	v_cvt_f32_f16_sdwa v37, v104 dst_sel:DWORD dst_unused:UNUSED_PAD src0_sel:WORD_1
	v_cvt_f32_f16_e32 v36, v104
	v_cvt_f32_f16_sdwa v129, v107 dst_sel:DWORD dst_unused:UNUSED_PAD src0_sel:WORD_1
	v_cvt_f32_f16_e32 v128, v107
	v_pk_fma_f32 v[112:113], v[56:57], v[82:83], v[120:121] op_sel_hi:[1,0,1] neg_lo:[0,0,1] neg_hi:[0,0,1]
	v_pk_fma_f32 v[56:57], v[38:39], v[82:83], v[16:17] op_sel_hi:[1,0,1] neg_lo:[0,0,1] neg_hi:[0,0,1]
	v_cvt_f32_f16_sdwa v17, v99 dst_sel:DWORD dst_unused:UNUSED_PAD src0_sel:WORD_1
	v_cvt_f32_f16_e32 v16, v99
	v_pk_fma_f32 v[116:117], v[54:55], v[82:83], v[124:125] op_sel_hi:[1,0,1] neg_lo:[0,0,1] neg_hi:[0,0,1]
	v_pk_fma_f32 v[54:55], v[34:35], v[82:83], v[36:37] op_sel_hi:[1,0,1] neg_lo:[0,0,1] neg_hi:[0,0,1]
	v_cvt_f32_f16_sdwa v35, v101 dst_sel:DWORD dst_unused:UNUSED_PAD src0_sel:WORD_1
	v_cvt_f32_f16_e32 v34, v101
	v_pk_fma_f32 v[120:121], v[64:65], v[82:83], v[128:129] op_sel_hi:[1,0,1] neg_lo:[0,0,1] neg_hi:[0,0,1]
	v_pk_mul_f32 v[58:59], v[110:111], v[110:111]
	v_pk_mul_f32 v[64:65], v[114:115], v[114:115]
	v_pk_mul_f32 v[124:125], v[116:117], v[116:117]
	v_pk_fma_f32 v[48:49], v[48:49], v[82:83], v[16:17] op_sel_hi:[1,0,1] neg_lo:[0,0,1] neg_hi:[0,0,1]
	v_cvt_f32_f16_sdwa v17, v98 dst_sel:DWORD dst_unused:UNUSED_PAD src0_sel:WORD_1
	v_cvt_f32_f16_e32 v16, v98
	v_add_f32_e32 v58, v58, v59
	v_add_f32_e32 v59, v64, v65
	v_pk_fma_f32 v[118:119], v[60:61], v[82:83], v[126:127] op_sel_hi:[1,0,1] neg_lo:[0,0,1] neg_hi:[0,0,1]
	v_pk_mul_f32 v[60:61], v[112:113], v[112:113]
	v_pk_fma_f32 v[44:45], v[44:45], v[82:83], v[34:35] op_sel_hi:[1,0,1] neg_lo:[0,0,1] neg_hi:[0,0,1]
	v_cvt_f32_f16_sdwa v35, v100 dst_sel:DWORD dst_unused:UNUSED_PAD src0_sel:WORD_1
	v_cvt_f32_f16_e32 v34, v100
	v_add_f32_e32 v58, v59, v58
	v_pk_mul_f32 v[106:107], v[122:123], v[122:123]
	v_add_f32_e32 v59, v60, v61
	s_waitcnt vmcnt(0)
	v_mov_b32_e32 v139, v68
	s_nop 1
	v_permlane32_swap_b32_e32 v66, v139
	v_mov_b32_e32 v141, v69
	v_lshlrev_b32_e32 v68, 16, v66
	v_and_b32_e32 v69, 0xffff0000, v66
	v_add_f32_e32 v66, v124, v125
	v_add_f32_e32 v58, v58, v66
	v_pk_mul_f32 v[126:127], v[118:119], v[118:119]
	v_add_f32_e32 v58, v58, v59
	v_add_f32_e32 v59, v106, v107
	v_pk_mul_f32 v[62:63], v[160:161], v[160:161]
	v_pk_fma_f32 v[46:47], v[46:47], v[82:83], v[16:17] op_sel_hi:[1,0,1] neg_lo:[0,0,1] neg_hi:[0,0,1]
	v_cvt_f32_f16_sdwa v17, v95 dst_sel:DWORD dst_unused:UNUSED_PAD src0_sel:WORD_1
	v_cvt_f32_f16_e32 v16, v95
	v_add_f32_e32 v58, v58, v59
	v_add_f32_e32 v59, v126, v127
	v_pk_mul_f32 v[128:129], v[120:121], v[120:121]
	v_pk_fma_f32 v[42:43], v[42:43], v[82:83], v[34:35] op_sel_hi:[1,0,1] neg_lo:[0,0,1] neg_hi:[0,0,1]
	v_cvt_f32_f16_sdwa v35, v97 dst_sel:DWORD dst_unused:UNUSED_PAD src0_sel:WORD_1
	v_cvt_f32_f16_e32 v34, v97
	v_add_f32_e32 v58, v58, v59
	v_add_f32_e32 v59, v62, v63
	v_pk_mul_f32 v[102:103], v[54:55], v[54:55]
	v_add_f32_e32 v58, v58, v59
	v_add_f32_e32 v59, v128, v129
	v_pk_mul_f32 v[104:105], v[50:51], v[50:51]
	v_add_f32_e32 v58, v58, v59
	v_add_f32_e32 v59, v102, v103
	v_pk_mul_f32 v[164:165], v[56:57], v[56:57]
	v_pk_fma_f32 v[36:37], v[24:25], v[82:83], v[16:17] op_sel_hi:[1,0,1] neg_lo:[0,0,1] neg_hi:[0,0,1]
	v_cvt_f32_f16_sdwa v17, v94 dst_sel:DWORD dst_unused:UNUSED_PAD src0_sel:WORD_1
	v_cvt_f32_f16_e32 v16, v94
	v_add_f32_e32 v58, v58, v59
	v_add_f32_e32 v59, v104, v105
	v_pk_mul_f32 v[162:163], v[52:53], v[52:53]
	v_pk_fma_f32 v[34:35], v[20:21], v[82:83], v[34:35] op_sel_hi:[1,0,1] neg_lo:[0,0,1] neg_hi:[0,0,1]
	v_cvt_f32_f16_sdwa v21, v96 dst_sel:DWORD dst_unused:UNUSED_PAD src0_sel:WORD_1
	v_cvt_f32_f16_e32 v20, v96
	v_add_f32_e32 v58, v58, v59
	v_add_f32_e32 v59, v164, v165
	v_pk_mul_f32 v[98:99], v[42:43], v[42:43]
	v_add_f32_e32 v58, v58, v59
	v_add_f32_e32 v59, v162, v163
	v_pk_mul_f32 v[100:101], v[44:45], v[44:45]
	v_add_f32_e32 v58, v58, v59
	v_add_f32_e32 v59, v98, v99
	v_pk_mul_f32 v[170:171], v[46:47], v[46:47]
	v_pk_fma_f32 v[40:41], v[22:23], v[82:83], v[16:17] op_sel_hi:[1,0,1] neg_lo:[0,0,1] neg_hi:[0,0,1]
	v_cvt_f32_f16_sdwa v17, v91 dst_sel:DWORD dst_unused:UNUSED_PAD src0_sel:WORD_1
	v_cvt_f32_f16_e32 v16, v91
	v_cvt_f32_f16_sdwa v23, v92 dst_sel:DWORD dst_unused:UNUSED_PAD src0_sel:WORD_1
	v_cvt_f32_f16_e32 v22, v92
	v_cvt_f32_f16_sdwa v91, v90 dst_sel:DWORD dst_unused:UNUSED_PAD src0_sel:WORD_1
	v_cvt_f32_f16_e32 v90, v90
	v_add_f32_e32 v58, v58, v59
	v_add_f32_e32 v59, v100, v101
	v_pk_mul_f32 v[168:169], v[48:49], v[48:49]
	v_pk_fma_f32 v[38:39], v[18:19], v[82:83], v[20:21] op_sel_hi:[1,0,1] neg_lo:[0,0,1] neg_hi:[0,0,1]
	v_add_f32_e32 v58, v58, v59
	v_add_f32_e32 v59, v170, v171
	v_cvt_f32_f16_sdwa v19, v93 dst_sel:DWORD dst_unused:UNUSED_PAD src0_sel:WORD_1
	v_cvt_f32_f16_e32 v18, v93
	v_pk_mul_f32 v[94:95], v[38:39], v[38:39]
	v_add_f32_e32 v58, v58, v59
	v_add_f32_e32 v59, v168, v169
	v_pk_mul_f32 v[96:97], v[34:35], v[34:35]
	v_add_f32_e32 v58, v58, v59
	v_add_f32_e32 v59, v94, v95
	v_pk_mul_f32 v[174:175], v[40:41], v[40:41]
	v_pk_fma_f32 v[20:21], v[32:33], v[82:83], v[16:17] op_sel_hi:[1,0,1] neg_lo:[0,0,1] neg_hi:[0,0,1]
	v_pk_fma_f32 v[24:25], v[26:27], v[82:83], v[22:23] op_sel_hi:[1,0,1] neg_lo:[0,0,1] neg_hi:[0,0,1]
	v_pk_fma_f32 v[22:23], v[30:31], v[82:83], v[90:91] op_sel_hi:[1,0,1] neg_lo:[0,0,1] neg_hi:[0,0,1]
	v_cvt_f32_f16_sdwa v33, v89 dst_sel:DWORD dst_unused:UNUSED_PAD src0_sel:WORD_1
	v_cvt_f32_f16_e32 v32, v89
	v_cvt_f32_f16_sdwa v91, v87 dst_sel:DWORD dst_unused:UNUSED_PAD src0_sel:WORD_1
	v_cvt_f32_f16_e32 v90, v87
	v_cvt_f32_f16_sdwa v89, v88 dst_sel:DWORD dst_unused:UNUSED_PAD src0_sel:WORD_1
	v_cvt_f32_f16_e32 v88, v88
	v_add_f32_e32 v58, v58, v59
	v_add_f32_e32 v59, v96, v97
	v_pk_mul_f32 v[172:173], v[36:37], v[36:37]
	v_add_f32_e32 v58, v58, v59
	v_add_f32_e32 v59, v174, v175
	v_pk_fma_f32 v[18:19], v[28:29], v[82:83], v[18:19] op_sel_hi:[1,0,1] neg_lo:[0,0,1] neg_hi:[0,0,1]
	v_pk_mul_f32 v[26:27], v[24:25], v[24:25]
	v_mov_b32_e32 v30, v23
	v_mov_b32_e32 v31, v21
	v_cvt_f32_f16_sdwa v87, v86 dst_sel:DWORD dst_unused:UNUSED_PAD src0_sel:WORD_1
	v_cvt_f32_f16_e32 v86, v86
	v_add_f32_e32 v58, v58, v59
	v_add_f32_e32 v59, v172, v173
	v_pk_mul_f32 v[28:29], v[18:19], v[18:19]
	v_mov_b32_e32 v16, v22
	v_mov_b32_e32 v17, v20
	v_pk_mul_f32 v[30:31], v[30:31], v[30:31]
	v_add_f32_e32 v58, v58, v59
	v_add_f32_e32 v26, v26, v27
	v_pk_fma_f32 v[30:31], v[16:17], v[16:17], v[30:31]
	v_pk_fma_f32 v[16:17], v[4:5], v[82:83], v[32:33] op_sel_hi:[1,0,1] neg_lo:[0,0,1] neg_hi:[0,0,1]
	v_pk_fma_f32 v[4:5], v[8:9], v[82:83], v[90:91] op_sel_hi:[1,0,1] neg_lo:[0,0,1] neg_hi:[0,0,1]
	v_pk_fma_f32 v[8:9], v[2:3], v[82:83], v[88:89] op_sel_hi:[1,0,1] neg_lo:[0,0,1] neg_hi:[0,0,1]
	v_add_f32_e32 v26, v58, v26
	v_add_f32_e32 v27, v28, v29
	v_mov_b32_e32 v32, v9
	v_mov_b32_e32 v33, v17
	v_add_f32_e32 v26, v26, v27
	v_mov_b32_e32 v2, v8
	v_mov_b32_e32 v3, v16
	v_pk_mul_f32 v[32:33], v[32:33], v[32:33]
	v_pk_fma_f32 v[6:7], v[6:7], v[82:83], v[86:87] op_sel_hi:[1,0,1] neg_lo:[0,0,1] neg_hi:[0,0,1]
	v_add_f32_e32 v26, v26, v30
	v_pk_fma_f32 v[2:3], v[2:3], v[2:3], v[32:33]
	v_mov_b32_e32 v82, v7
	v_mov_b32_e32 v83, v5
	v_add_f32_e32 v26, v26, v31
	v_mov_b32_e32 v32, v6
	v_mov_b32_e32 v33, v4
	v_pk_mul_f32 v[82:83], v[82:83], v[82:83]
	v_add_f32_e32 v2, v26, v2
	v_pk_fma_f32 v[32:33], v[32:33], v[32:33], v[82:83]
	v_add_f32_e32 v2, v2, v3
	v_add_f32_e32 v2, v2, v32
	v_add_f32_e32 v2, v2, v33
	v_add_f32_e32 v2, v2, v142
	v_add_f32_e32 v2, v2, v143
	v_add_f32_e32 v2, v2, v146
	v_add_f32_e32 v2, v2, v147
	ds_bpermute_b32 v3, v1, v2
	v_permlane32_swap_b32_e32 v67, v141
	v_lshlrev_b32_e32 v30, 16, v67
	v_and_b32_e32 v31, 0xffff0000, v67
	s_waitcnt lgkmcnt(0)
	v_add_f32_e32 v2, v2, v3
	v_fmamk_f32 v2, v2, 0x3c000000, v157
	v_mul_f32_e32 v3, 0x4b800000, v2
	v_cmp_gt_f32_e32 vcc, s38, v2
	v_lshlrev_b32_e32 v32, 16, v139
	v_and_b32_e32 v33, 0xffff0000, v139
	v_cndmask_b32_e32 v2, v2, v3, vcc
	v_rsq_f32_e32 v2, v2
	v_lshlrev_b32_e32 v58, 16, v141
	v_and_b32_e32 v59, 0xffff0000, v141
	v_lshl_add_u64 v[10:11], v[78:79], 0, s[20:21]
	v_mul_f32_e32 v3, 0x45800000, v2
	v_cndmask_b32_e32 v2, v2, v3, vcc
	v_mul_f32_e32 v2, 0x3f4ccccd, v2
	v_pk_mul_f32 v[62:63], v[110:111], v[2:3] op_sel_hi:[1,0]
	v_pk_mul_f32 v[60:61], v[114:115], v[2:3] op_sel_hi:[1,0]
	v_pk_mul_f32 v[62:63], v[76:77], v[62:63]
	v_pk_mul_f32 v[60:61], v[74:75], v[60:61]
	v_pk_mul_f32 v[62:63], v[62:63], v[30:31]
	v_pk_mul_f32 v[30:31], v[116:117], v[2:3] op_sel_hi:[1,0]
	v_pk_mul_f32 v[60:61], v[60:61], v[68:69]
	v_pk_mul_f32 v[30:31], v[70:71], v[30:31]
	global_load_dwordx4 v[196:199], v[10:11], off offset:224
	global_load_dwordx4 v[200:203], v[10:11], off offset:32
	global_load_dwordx4 v[204:207], v[10:11], off offset:64
	global_load_dwordx4 v[208:211], v[10:11], off offset:96
	global_load_dwordx4 v[212:215], v[10:11], off offset:128
	global_load_dwordx4 v[216:219], v[10:11], off offset:160
	global_load_dwordx4 v[220:223], v[10:11], off offset:192
	v_pk_mul_f32 v[32:33], v[30:31], v[32:33]
	v_pk_mul_f32 v[30:31], v[112:113], v[2:3] op_sel_hi:[1,0]
	v_and_b32_sdwa v3, v61, v158 dst_sel:DWORD dst_unused:UNUSED_PAD src0_sel:WORD_1 src1_sel:DWORD
	v_pk_mul_f32 v[30:31], v[72:73], v[30:31]
	v_add3_u32 v3, v61, v3, s39
	v_pk_mul_f32 v[58:59], v[30:31], v[58:59]
	v_and_b32_sdwa v30, v60, v158 dst_sel:DWORD dst_unused:UNUSED_PAD src0_sel:WORD_1 src1_sel:DWORD
	v_add3_u32 v30, v60, v30, s39
	v_lshrrev_b32_e32 v30, 16, v30
	v_and_b32_sdwa v31, v32, v158 dst_sel:DWORD dst_unused:UNUSED_PAD src0_sel:WORD_1 src1_sel:DWORD
	v_and_or_b32 v30, v3, s35, v30
	v_and_b32_sdwa v3, v33, v158 dst_sel:DWORD dst_unused:UNUSED_PAD src0_sel:WORD_1 src1_sel:DWORD
	v_add3_u32 v31, v32, v31, s39
	v_add3_u32 v3, v33, v3, s39
	v_lshrrev_b32_e32 v31, 16, v31
	v_and_or_b32 v32, v3, s35, v31
	v_and_b32_sdwa v31, v62, v158 dst_sel:DWORD dst_unused:UNUSED_PAD src0_sel:WORD_1 src1_sel:DWORD
	v_and_b32_sdwa v3, v63, v158 dst_sel:DWORD dst_unused:UNUSED_PAD src0_sel:WORD_1 src1_sel:DWORD
	v_add3_u32 v31, v62, v31, s39
	v_add3_u32 v3, v63, v3, s39
	v_lshrrev_b32_e32 v31, 16, v31
	v_and_b32_sdwa v33, v58, v158 dst_sel:DWORD dst_unused:UNUSED_PAD src0_sel:WORD_1 src1_sel:DWORD
	v_and_or_b32 v31, v3, s35, v31
	v_and_b32_sdwa v3, v59, v158 dst_sel:DWORD dst_unused:UNUSED_PAD src0_sel:WORD_1 src1_sel:DWORD
	v_add3_u32 v33, v58, v33, s39
	v_add3_u32 v3, v59, v3, s39
	v_lshrrev_b32_e32 v33, 16, v33
	v_and_or_b32 v33, v3, s35, v33
	v_permlane32_swap_b32_e32 v30, v32
	s_nop 0
	v_permlane32_swap_b32_e32 v31, v33
	global_store_dwordx4 v[84:85], v[30:33], off offset:2048
	ds_read_b128 v[30:33], v193 offset:64
	s_nop 0
	ds_read_b128 v[58:61], v193 offset:96
	s_waitcnt vmcnt(6)
	s_nop 1
	v_mov_b32_e32 v78, v196
	v_mov_b32_e32 v79, v197
	v_mov_b32_e32 v80, v198
	v_mov_b32_e32 v81, v199
	v_mov_b32_e32 v26, v200
	v_mov_b32_e32 v27, v201
	v_mov_b32_e32 v28, v202
	v_mov_b32_e32 v29, v203
	s_nop 1
	v_mov_b32_e32 v3, v28
	s_nop 1
	v_permlane32_swap_b32_e32 v26, v3
	v_pk_mul_f32 v[70:71], v[122:123], v[2:3] op_sel_hi:[1,0]
	v_mov_b32_e32 v69, v29
	v_lshlrev_b32_e32 v28, 16, v26
	v_and_b32_e32 v29, 0xffff0000, v26
	v_permlane32_swap_b32_e32 v27, v69
	v_lshlrev_b32_e32 v26, 16, v27
	v_and_b32_e32 v27, 0xffff0000, v27
	v_lshlrev_b32_e32 v66, 16, v3
	v_and_b32_e32 v67, 0xffff0000, v3
	v_lshlrev_b32_e32 v68, 16, v69
	v_and_b32_e32 v69, 0xffff0000, v69
	s_waitcnt lgkmcnt(1)
	v_pk_mul_f32 v[30:31], v[30:31], v[70:71]
	s_nop 0
	v_pk_mul_f32 v[28:29], v[30:31], v[28:29]
	v_pk_mul_f32 v[30:31], v[118:119], v[2:3] op_sel_hi:[1,0]
	s_nop 0
	v_pk_mul_f32 v[30:31], v[32:33], v[30:31]
	s_nop 0
	v_pk_mul_f32 v[30:31], v[30:31], v[26:27]
	v_pk_mul_f32 v[26:27], v[160:161], v[2:3] op_sel_hi:[1,0]
	s_waitcnt lgkmcnt(0)
	v_pk_mul_f32 v[26:27], v[58:59], v[26:27]
	s_nop 0
	v_pk_mul_f32 v[32:33], v[26:27], v[66:67]
	v_pk_mul_f32 v[26:27], v[120:121], v[2:3] op_sel_hi:[1,0]
	v_and_b32_sdwa v3, v29, v158 dst_sel:DWORD dst_unused:UNUSED_PAD src0_sel:WORD_1 src1_sel:DWORD
	v_pk_mul_f32 v[26:27], v[60:61], v[26:27]
	v_add3_u32 v3, v29, v3, s39
	v_pk_mul_f32 v[58:59], v[26:27], v[68:69]
	v_and_b32_sdwa v26, v28, v158 dst_sel:DWORD dst_unused:UNUSED_PAD src0_sel:WORD_1 src1_sel:DWORD
	v_add3_u32 v26, v28, v26, s39
	v_lshrrev_b32_e32 v26, 16, v26
	v_and_b32_sdwa v27, v32, v158 dst_sel:DWORD dst_unused:UNUSED_PAD src0_sel:WORD_1 src1_sel:DWORD
	v_and_or_b32 v26, v3, s35, v26
	v_and_b32_sdwa v3, v33, v158 dst_sel:DWORD dst_unused:UNUSED_PAD src0_sel:WORD_1 src1_sel:DWORD
	v_add3_u32 v27, v32, v27, s39
	v_add3_u32 v3, v33, v3, s39
	v_lshrrev_b32_e32 v27, 16, v27
	v_and_or_b32 v28, v3, s35, v27
	v_and_b32_sdwa v27, v30, v158 dst_sel:DWORD dst_unused:UNUSED_PAD src0_sel:WORD_1 src1_sel:DWORD
	v_and_b32_sdwa v3, v31, v158 dst_sel:DWORD dst_unused:UNUSED_PAD src0_sel:WORD_1 src1_sel:DWORD
	v_add3_u32 v27, v30, v27, s39
	v_add3_u32 v3, v31, v3, s39
	v_lshrrev_b32_e32 v27, 16, v27
	v_and_b32_sdwa v29, v58, v158 dst_sel:DWORD dst_unused:UNUSED_PAD src0_sel:WORD_1 src1_sel:DWORD
	v_and_or_b32 v27, v3, s35, v27
	v_and_b32_sdwa v3, v59, v158 dst_sel:DWORD dst_unused:UNUSED_PAD src0_sel:WORD_1 src1_sel:DWORD
	v_add3_u32 v29, v58, v29, s39
	v_add3_u32 v3, v59, v3, s39
	v_lshrrev_b32_e32 v29, 16, v29
	v_and_or_b32 v29, v3, s35, v29
	v_permlane32_swap_b32_e32 v26, v28
	s_nop 0
	v_permlane32_swap_b32_e32 v27, v29
	global_store_dwordx4 v[10:11], v[26:29], off offset:32
	ds_read_b128 v[26:29], v193 offset:128
	s_nop 0
	ds_read_b128 v[30:33], v193 offset:160
	s_waitcnt vmcnt(6)
	s_nop 1
	v_mov_b32_e32 v62, v204
	v_mov_b32_e32 v63, v205
	v_mov_b32_e32 v64, v206
	v_mov_b32_e32 v65, v207
	s_nop 1
	v_mov_b32_e32 v3, v64
	s_nop 1
	v_permlane32_swap_b32_e32 v62, v3
	v_mov_b32_e32 v58, v65
	s_nop 1
	v_permlane32_swap_b32_e32 v63, v58
	v_pk_mul_f32 v[50:51], v[50:51], v[2:3] op_sel_hi:[1,0]
	v_lshlrev_b32_e32 v64, 16, v62
	v_and_b32_e32 v65, 0xffff0000, v62
	v_lshlrev_b32_e32 v62, 16, v63
	v_and_b32_e32 v63, 0xffff0000, v63
	v_pk_mul_f32 v[54:55], v[54:55], v[2:3] op_sel_hi:[1,0]
	v_lshlrev_b32_e32 v66, 16, v3
	v_and_b32_e32 v67, 0xffff0000, v3
	v_lshlrev_b32_e32 v68, 16, v58
	v_and_b32_e32 v69, 0xffff0000, v58
	s_waitcnt lgkmcnt(1)
	v_pk_mul_f32 v[28:29], v[50:51], v[28:29]
	v_pk_mul_f32 v[26:27], v[54:55], v[26:27]
	v_pk_mul_f32 v[50:51], v[28:29], v[62:63]
	v_pk_mul_f32 v[28:29], v[56:57], v[2:3] op_sel_hi:[1,0]
	v_pk_mul_f32 v[26:27], v[26:27], v[64:65]
	s_waitcnt lgkmcnt(0)
	v_pk_mul_f32 v[28:29], v[28:29], v[30:31]
	v_pk_mul_f32 v[30:31], v[52:53], v[2:3] op_sel_hi:[1,0]
	v_pk_mul_f32 v[28:29], v[28:29], v[66:67]
	v_pk_mul_f32 v[30:31], v[30:31], v[32:33]
	v_and_b32_sdwa v32, v26, v158 dst_sel:DWORD dst_unused:UNUSED_PAD src0_sel:WORD_1 src1_sel:DWORD
	v_and_b32_sdwa v3, v27, v158 dst_sel:DWORD dst_unused:UNUSED_PAD src0_sel:WORD_1 src1_sel:DWORD
	v_add3_u32 v26, v26, v32, s39
	v_add3_u32 v3, v27, v3, s39
	v_lshrrev_b32_e32 v26, 16, v26
	v_and_b32_sdwa v27, v28, v158 dst_sel:DWORD dst_unused:UNUSED_PAD src0_sel:WORD_1 src1_sel:DWORD
	v_and_or_b32 v26, v3, s35, v26
	v_and_b32_sdwa v3, v29, v158 dst_sel:DWORD dst_unused:UNUSED_PAD src0_sel:WORD_1 src1_sel:DWORD
	v_add3_u32 v27, v28, v27, s39
	v_add3_u32 v3, v29, v3, s39
	v_lshrrev_b32_e32 v27, 16, v27
	v_and_or_b32 v28, v3, s35, v27
	v_and_b32_sdwa v27, v50, v158 dst_sel:DWORD dst_unused:UNUSED_PAD src0_sel:WORD_1 src1_sel:DWORD
	v_pk_mul_f32 v[30:31], v[30:31], v[68:69]
	v_and_b32_sdwa v3, v51, v158 dst_sel:DWORD dst_unused:UNUSED_PAD src0_sel:WORD_1 src1_sel:DWORD
	v_add3_u32 v27, v50, v27, s39
	v_add3_u32 v3, v51, v3, s39
	v_lshrrev_b32_e32 v27, 16, v27
	v_and_b32_sdwa v29, v30, v158 dst_sel:DWORD dst_unused:UNUSED_PAD src0_sel:WORD_1 src1_sel:DWORD
	v_and_or_b32 v27, v3, s35, v27
	v_and_b32_sdwa v3, v31, v158 dst_sel:DWORD dst_unused:UNUSED_PAD src0_sel:WORD_1 src1_sel:DWORD
	v_add3_u32 v29, v30, v29, s39
	v_add3_u32 v3, v31, v3, s39
	v_lshrrev_b32_e32 v29, 16, v29
	v_and_or_b32 v29, v3, s35, v29
	v_permlane32_swap_b32_e32 v26, v28
	s_nop 0
	v_permlane32_swap_b32_e32 v27, v29
	global_store_dwordx4 v[10:11], v[26:29], off offset:64
	ds_read_b128 v[26:29], v193 offset:192
	s_nop 0
	ds_read_b128 v[30:33], v193 offset:224
	s_waitcnt vmcnt(6)
	s_nop 1
	v_mov_b32_e32 v58, v208
	v_mov_b32_e32 v59, v209
	v_mov_b32_e32 v60, v210
	v_mov_b32_e32 v61, v211
	s_nop 1
	v_mov_b32_e32 v3, v60
	s_nop 1
	v_permlane32_swap_b32_e32 v58, v3
	v_pk_mul_f32 v[42:43], v[42:43], v[2:3] op_sel_hi:[1,0]
	v_permlane32_swap_b32_e32 v59, v61
	v_lshlrev_b32_e32 v56, 16, v59
	v_and_b32_e32 v57, 0xffff0000, v59
	v_lshlrev_b32_e32 v54, 16, v58
	v_and_b32_e32 v55, 0xffff0000, v58
	v_lshlrev_b32_e32 v58, 16, v3
	v_and_b32_e32 v59, 0xffff0000, v3
	v_lshlrev_b32_e32 v60, 16, v61
	v_and_b32_e32 v61, 0xffff0000, v61
	s_waitcnt lgkmcnt(1)
	v_pk_mul_f32 v[26:27], v[42:43], v[26:27]
	v_pk_mul_f32 v[42:43], v[44:45], v[2:3] op_sel_hi:[1,0]
	v_pk_mul_f32 v[26:27], v[26:27], v[54:55]
	v_pk_mul_f32 v[28:29], v[42:43], v[28:29]
	s_nop 0
	v_pk_mul_f32 v[42:43], v[28:29], v[56:57]
	v_pk_mul_f32 v[28:29], v[46:47], v[2:3] op_sel_hi:[1,0]
	s_waitcnt lgkmcnt(0)
	v_pk_mul_f32 v[28:29], v[28:29], v[30:31]
	v_pk_mul_f32 v[30:31], v[48:49], v[2:3] op_sel_hi:[1,0]
	v_pk_mul_f32 v[28:29], v[28:29], v[58:59]
	v_pk_mul_f32 v[30:31], v[30:31], v[32:33]
	v_and_b32_sdwa v32, v26, v158 dst_sel:DWORD dst_unused:UNUSED_PAD src0_sel:WORD_1 src1_sel:DWORD
	v_and_b32_sdwa v3, v27, v158 dst_sel:DWORD dst_unused:UNUSED_PAD src0_sel:WORD_1 src1_sel:DWORD
	v_add3_u32 v26, v26, v32, s39
	v_add3_u32 v3, v27, v3, s39
	v_lshrrev_b32_e32 v26, 16, v26
	v_and_b32_sdwa v27, v28, v158 dst_sel:DWORD dst_unused:UNUSED_PAD src0_sel:WORD_1 src1_sel:DWORD
	v_and_or_b32 v26, v3, s35, v26
	v_and_b32_sdwa v3, v29, v158 dst_sel:DWORD dst_unused:UNUSED_PAD src0_sel:WORD_1 src1_sel:DWORD
	v_add3_u32 v27, v28, v27, s39
	v_add3_u32 v3, v29, v3, s39
	v_lshrrev_b32_e32 v27, 16, v27
	v_and_or_b32 v28, v3, s35, v27
	v_and_b32_sdwa v27, v42, v158 dst_sel:DWORD dst_unused:UNUSED_PAD src0_sel:WORD_1 src1_sel:DWORD
	v_pk_mul_f32 v[30:31], v[30:31], v[60:61]
	v_and_b32_sdwa v3, v43, v158 dst_sel:DWORD dst_unused:UNUSED_PAD src0_sel:WORD_1 src1_sel:DWORD
	v_add3_u32 v27, v42, v27, s39
	v_add3_u32 v3, v43, v3, s39
	v_lshrrev_b32_e32 v27, 16, v27
	v_and_b32_sdwa v29, v30, v158 dst_sel:DWORD dst_unused:UNUSED_PAD src0_sel:WORD_1 src1_sel:DWORD
	v_and_or_b32 v27, v3, s35, v27
	v_and_b32_sdwa v3, v31, v158 dst_sel:DWORD dst_unused:UNUSED_PAD src0_sel:WORD_1 src1_sel:DWORD
	v_add3_u32 v29, v30, v29, s39
	v_add3_u32 v3, v31, v3, s39
	v_lshrrev_b32_e32 v29, 16, v29
	v_and_or_b32 v29, v3, s35, v29
	v_permlane32_swap_b32_e32 v26, v28
	s_nop 0
	v_permlane32_swap_b32_e32 v27, v29
	global_store_dwordx4 v[10:11], v[26:29], off offset:96
	ds_read_b128 v[26:29], v193 offset:256
	s_nop 0
	ds_read_b128 v[30:33], v193 offset:288
	s_waitcnt vmcnt(6)
	s_nop 1
	v_mov_b32_e32 v50, v212
	v_mov_b32_e32 v51, v213
	v_mov_b32_e32 v52, v214
	v_mov_b32_e32 v53, v215
	s_nop 1
	v_mov_b32_e32 v3, v52
	s_nop 1
	v_permlane32_swap_b32_e32 v50, v3
	v_mov_b32_e32 v42, v53
	s_nop 1
	v_permlane32_swap_b32_e32 v51, v42
	v_pk_mul_f32 v[34:35], v[34:35], v[2:3] op_sel_hi:[1,0]
	v_lshlrev_b32_e32 v48, 16, v51
	v_and_b32_e32 v49, 0xffff0000, v51
	v_pk_mul_f32 v[38:39], v[38:39], v[2:3] op_sel_hi:[1,0]
	v_lshlrev_b32_e32 v46, 16, v50
	v_and_b32_e32 v47, 0xffff0000, v50
	v_lshlrev_b32_e32 v50, 16, v3
	v_and_b32_e32 v51, 0xffff0000, v3
	v_lshlrev_b32_e32 v52, 16, v42
	v_and_b32_e32 v53, 0xffff0000, v42
	s_waitcnt lgkmcnt(1)
	v_pk_mul_f32 v[28:29], v[34:35], v[28:29]
	v_pk_mul_f32 v[26:27], v[38:39], v[26:27]
	v_pk_mul_f32 v[34:35], v[28:29], v[48:49]
	v_pk_mul_f32 v[28:29], v[40:41], v[2:3] op_sel_hi:[1,0]
	v_pk_mul_f32 v[26:27], v[26:27], v[46:47]
	s_waitcnt lgkmcnt(0)
	v_pk_mul_f32 v[28:29], v[28:29], v[30:31]
	v_pk_mul_f32 v[30:31], v[36:37], v[2:3] op_sel_hi:[1,0]
	v_pk_mul_f32 v[28:29], v[28:29], v[50:51]
	v_pk_mul_f32 v[30:31], v[30:31], v[32:33]
	v_and_b32_sdwa v32, v26, v158 dst_sel:DWORD dst_unused:UNUSED_PAD src0_sel:WORD_1 src1_sel:DWORD
	v_and_b32_sdwa v3, v27, v158 dst_sel:DWORD dst_unused:UNUSED_PAD src0_sel:WORD_1 src1_sel:DWORD
	v_add3_u32 v26, v26, v32, s39
	v_add3_u32 v3, v27, v3, s39
	v_lshrrev_b32_e32 v26, 16, v26
	v_and_b32_sdwa v27, v28, v158 dst_sel:DWORD dst_unused:UNUSED_PAD src0_sel:WORD_1 src1_sel:DWORD
	v_and_or_b32 v26, v3, s35, v26
	v_and_b32_sdwa v3, v29, v158 dst_sel:DWORD dst_unused:UNUSED_PAD src0_sel:WORD_1 src1_sel:DWORD
	v_add3_u32 v27, v28, v27, s39
	v_add3_u32 v3, v29, v3, s39
	v_lshrrev_b32_e32 v27, 16, v27
	v_and_or_b32 v28, v3, s35, v27
	v_and_b32_sdwa v27, v34, v158 dst_sel:DWORD dst_unused:UNUSED_PAD src0_sel:WORD_1 src1_sel:DWORD
	v_pk_mul_f32 v[30:31], v[30:31], v[52:53]
	v_and_b32_sdwa v3, v35, v158 dst_sel:DWORD dst_unused:UNUSED_PAD src0_sel:WORD_1 src1_sel:DWORD
	v_add3_u32 v27, v34, v27, s39
	v_add3_u32 v3, v35, v3, s39
	v_lshrrev_b32_e32 v27, 16, v27
	v_and_b32_sdwa v29, v30, v158 dst_sel:DWORD dst_unused:UNUSED_PAD src0_sel:WORD_1 src1_sel:DWORD
	v_and_or_b32 v27, v3, s35, v27
	v_and_b32_sdwa v3, v31, v158 dst_sel:DWORD dst_unused:UNUSED_PAD src0_sel:WORD_1 src1_sel:DWORD
	v_add3_u32 v29, v30, v29, s39
	v_add3_u32 v3, v31, v3, s39
	v_lshrrev_b32_e32 v29, 16, v29
	v_and_or_b32 v29, v3, s35, v29
	v_permlane32_swap_b32_e32 v26, v28
	s_nop 0
	v_permlane32_swap_b32_e32 v27, v29
	global_store_dwordx4 v[10:11], v[26:29], off offset:128
	ds_read_b128 v[26:29], v193 offset:320
	s_nop 0
	ds_read_b128 v[30:33], v193 offset:352
	s_waitcnt vmcnt(6)
	s_nop 1
	v_mov_b32_e32 v42, v216
	v_mov_b32_e32 v43, v217
	v_mov_b32_e32 v44, v218
	v_mov_b32_e32 v45, v219
	s_nop 1
	v_mov_b32_e32 v3, v44
	s_nop 1
	v_permlane32_swap_b32_e32 v42, v3
	v_permlane32_swap_b32_e32 v43, v45
	v_pk_mul_f32 v[18:19], v[18:19], v[2:3] op_sel_hi:[1,0]
	v_lshlrev_b32_e32 v40, 16, v43
	v_and_b32_e32 v41, 0xffff0000, v43
	v_pk_mul_f32 v[24:25], v[24:25], v[2:3] op_sel_hi:[1,0]
	v_lshlrev_b32_e32 v38, 16, v42
	v_and_b32_e32 v39, 0xffff0000, v42
	v_lshlrev_b32_e32 v42, 16, v3
	v_and_b32_e32 v43, 0xffff0000, v3
	v_lshlrev_b32_e32 v44, 16, v45
	v_and_b32_e32 v45, 0xffff0000, v45
	s_waitcnt lgkmcnt(1)
	v_pk_mul_f32 v[18:19], v[18:19], v[28:29]
	v_pk_mul_f32 v[24:25], v[24:25], v[26:27]
	v_pk_mul_f32 v[26:27], v[18:19], v[40:41]
	v_pk_mul_f32 v[18:19], v[22:23], v[2:3] op_sel_hi:[1,0]
	v_pk_mul_f32 v[24:25], v[24:25], v[38:39]
	s_waitcnt lgkmcnt(0)
	v_pk_mul_f32 v[18:19], v[18:19], v[30:31]
	s_nop 0
	v_pk_mul_f32 v[22:23], v[18:19], v[42:43]
	v_pk_mul_f32 v[18:19], v[20:21], v[2:3] op_sel_hi:[1,0]
	v_and_b32_sdwa v3, v25, v158 dst_sel:DWORD dst_unused:UNUSED_PAD src0_sel:WORD_1 src1_sel:DWORD
	v_pk_mul_f32 v[18:19], v[18:19], v[32:33]
	v_add3_u32 v3, v25, v3, s39
	v_pk_mul_f32 v[28:29], v[18:19], v[44:45]
	v_and_b32_sdwa v18, v24, v158 dst_sel:DWORD dst_unused:UNUSED_PAD src0_sel:WORD_1 src1_sel:DWORD
	v_add3_u32 v18, v24, v18, s39
	v_lshrrev_b32_e32 v18, 16, v18
	v_and_b32_sdwa v19, v22, v158 dst_sel:DWORD dst_unused:UNUSED_PAD src0_sel:WORD_1 src1_sel:DWORD
	v_and_or_b32 v18, v3, s35, v18
	v_and_b32_sdwa v3, v23, v158 dst_sel:DWORD dst_unused:UNUSED_PAD src0_sel:WORD_1 src1_sel:DWORD
	v_add3_u32 v19, v22, v19, s39
	v_add3_u32 v3, v23, v3, s39
	v_lshrrev_b32_e32 v19, 16, v19
	v_and_or_b32 v20, v3, s35, v19
	v_and_b32_sdwa v19, v26, v158 dst_sel:DWORD dst_unused:UNUSED_PAD src0_sel:WORD_1 src1_sel:DWORD
	v_and_b32_sdwa v3, v27, v158 dst_sel:DWORD dst_unused:UNUSED_PAD src0_sel:WORD_1 src1_sel:DWORD
	v_add3_u32 v19, v26, v19, s39
	v_add3_u32 v3, v27, v3, s39
	v_lshrrev_b32_e32 v19, 16, v19
	v_and_b32_sdwa v21, v28, v158 dst_sel:DWORD dst_unused:UNUSED_PAD src0_sel:WORD_1 src1_sel:DWORD
	v_and_or_b32 v19, v3, s35, v19
	v_and_b32_sdwa v3, v29, v158 dst_sel:DWORD dst_unused:UNUSED_PAD src0_sel:WORD_1 src1_sel:DWORD
	v_add3_u32 v21, v28, v21, s39
	v_add3_u32 v3, v29, v3, s39
	v_lshrrev_b32_e32 v21, 16, v21
	v_and_or_b32 v21, v3, s35, v21
	v_permlane32_swap_b32_e32 v18, v20
	s_nop 0
	v_permlane32_swap_b32_e32 v19, v21
	global_store_dwordx4 v[10:11], v[18:21], off offset:160
	ds_read_b128 v[18:21], v193 offset:384
	s_nop 0
	ds_read_b128 v[22:25], v193 offset:416
	v_pk_mul_f32 v[8:9], v[8:9], v[2:3] op_sel_hi:[1,0]
	v_pk_mul_f32 v[16:17], v[16:17], v[2:3] op_sel_hi:[1,0]
	v_pk_mul_f32 v[6:7], v[6:7], v[2:3] op_sel_hi:[1,0]
	v_pk_mul_f32 v[4:5], v[4:5], v[2:3] op_sel_hi:[1,0]
	s_waitcnt vmcnt(6)
	s_nop 1
	v_mov_b32_e32 v34, v220
	v_mov_b32_e32 v35, v221
	v_mov_b32_e32 v36, v222
	v_mov_b32_e32 v37, v223
	s_nop 1
	v_mov_b32_e32 v3, v36
	v_mov_b32_e32 v33, v37
	s_nop 0
	v_permlane32_swap_b32_e32 v34, v3
	v_permlane32_swap_b32_e32 v35, v33
	v_lshlrev_b32_e32 v26, 16, v34
	v_and_b32_e32 v27, 0xffff0000, v34
	v_lshlrev_b32_e32 v32, 16, v33
	v_and_b32_e32 v33, 0xffff0000, v33
	v_lshlrev_b32_e32 v30, 16, v3
	v_and_b32_e32 v31, 0xffff0000, v3
	v_lshlrev_b32_e32 v28, 16, v35
	v_and_b32_e32 v29, 0xffff0000, v35
	s_waitcnt lgkmcnt(1)
	v_pk_mul_f32 v[8:9], v[8:9], v[18:19]
	s_waitcnt lgkmcnt(0)
	v_pk_mul_f32 v[4:5], v[4:5], v[24:25]
	v_pk_mul_f32 v[8:9], v[8:9], v[26:27]
	v_pk_mul_f32 v[18:19], v[4:5], v[32:33]
	v_and_b32_sdwa v4, v8, v158 dst_sel:DWORD dst_unused:UNUSED_PAD src0_sel:WORD_1 src1_sel:DWORD
	v_pk_mul_f32 v[6:7], v[6:7], v[22:23]
	v_and_b32_sdwa v3, v9, v158 dst_sel:DWORD dst_unused:UNUSED_PAD src0_sel:WORD_1 src1_sel:DWORD
	v_add3_u32 v4, v8, v4, s39
	v_pk_mul_f32 v[6:7], v[6:7], v[30:31]
	v_add3_u32 v3, v9, v3, s39
	v_lshrrev_b32_e32 v4, 16, v4
	v_and_or_b32 v4, v3, s35, v4
	v_and_b32_sdwa v3, v6, v158 dst_sel:DWORD dst_unused:UNUSED_PAD src0_sel:WORD_1 src1_sel:DWORD
	v_pk_mul_f32 v[16:17], v[16:17], v[20:21]
	v_and_b32_sdwa v5, v7, v158 dst_sel:DWORD dst_unused:UNUSED_PAD src0_sel:WORD_1 src1_sel:DWORD
	v_add3_u32 v3, v6, v3, s39
	v_pk_mul_f32 v[16:17], v[16:17], v[28:29]
	v_add3_u32 v5, v7, v5, s39
	v_lshrrev_b32_e32 v3, 16, v3
	v_and_or_b32 v6, v5, s35, v3
	v_and_b32_sdwa v5, v16, v158 dst_sel:DWORD dst_unused:UNUSED_PAD src0_sel:WORD_1 src1_sel:DWORD
	v_and_b32_sdwa v3, v17, v158 dst_sel:DWORD dst_unused:UNUSED_PAD src0_sel:WORD_1 src1_sel:DWORD
	v_add3_u32 v5, v16, v5, s39
	v_add3_u32 v3, v17, v3, s39
	v_lshrrev_b32_e32 v5, 16, v5
	v_and_b32_sdwa v7, v18, v158 dst_sel:DWORD dst_unused:UNUSED_PAD src0_sel:WORD_1 src1_sel:DWORD
	v_and_or_b32 v5, v3, s35, v5
	v_and_b32_sdwa v3, v19, v158 dst_sel:DWORD dst_unused:UNUSED_PAD src0_sel:WORD_1 src1_sel:DWORD
	v_add3_u32 v7, v18, v7, s39
	v_add3_u32 v3, v19, v3, s39
	v_lshrrev_b32_e32 v7, 16, v7
	v_and_or_b32 v7, v3, s35, v7
	v_permlane32_swap_b32_e32 v4, v6
	s_nop 0
	v_permlane32_swap_b32_e32 v5, v7
	global_store_dwordx4 v[10:11], v[4:7], off offset:192
	ds_read_b128 v[4:7], v193 offset:448
	s_nop 0
	ds_read_b128 v[16:19], v193 offset:480
	v_mov_b32_e32 v8, v144
	v_mov_b32_e32 v9, v14
	v_mov_b32_e32 v20, v108
	v_mov_b32_e32 v21, v12
	v_mov_b32_e32 v14, v145
	v_mov_b32_e32 v12, v109
	v_mov_b32_e32 v25, v80
	v_mov_b32_e32 v27, v81
	v_pk_mul_f32 v[8:9], v[8:9], v[2:3] op_sel_hi:[1,0]
	v_pk_mul_f32 v[20:21], v[20:21], v[2:3] op_sel_hi:[1,0]
	v_pk_mul_f32 v[14:15], v[14:15], v[2:3] op_sel_hi:[1,0]
	v_pk_mul_f32 v[2:3], v[12:13], v[2:3] op_sel_hi:[1,0]
	v_permlane32_swap_b32_e32 v78, v25
	v_permlane32_swap_b32_e32 v79, v27
	v_lshlrev_b32_e32 v12, 16, v78
	v_and_b32_e32 v13, 0xffff0000, v78
	v_lshlrev_b32_e32 v22, 16, v79
	v_and_b32_e32 v23, 0xffff0000, v79
	v_lshlrev_b32_e32 v24, 16, v25
	v_and_b32_e32 v25, 0xffff0000, v25
	v_lshlrev_b32_e32 v26, 16, v27
	v_and_b32_e32 v27, 0xffff0000, v27
	s_waitcnt lgkmcnt(1)
	v_pk_mul_f32 v[4:5], v[8:9], v[4:5]
	s_waitcnt lgkmcnt(0)
	v_pk_mul_f32 v[8:9], v[20:21], v[16:17]
	v_pk_mul_f32 v[6:7], v[14:15], v[6:7]
	v_pk_mul_f32 v[2:3], v[2:3], v[18:19]
	v_pk_mul_f32 v[4:5], v[4:5], v[12:13]
	v_pk_mul_f32 v[8:9], v[8:9], v[24:25]
	v_pk_mul_f32 v[6:7], v[6:7], v[22:23]
	v_pk_mul_f32 v[2:3], v[2:3], v[26:27]
	v_and_b32_sdwa v13, v4, v158 dst_sel:DWORD dst_unused:UNUSED_PAD src0_sel:WORD_1 src1_sel:DWORD
	v_and_b32_sdwa v15, v8, v158 dst_sel:DWORD dst_unused:UNUSED_PAD src0_sel:WORD_1 src1_sel:DWORD
	v_and_b32_sdwa v17, v6, v158 dst_sel:DWORD dst_unused:UNUSED_PAD src0_sel:WORD_1 src1_sel:DWORD
	v_and_b32_sdwa v19, v2, v158 dst_sel:DWORD dst_unused:UNUSED_PAD src0_sel:WORD_1 src1_sel:DWORD
	v_and_b32_sdwa v12, v5, v158 dst_sel:DWORD dst_unused:UNUSED_PAD src0_sel:WORD_1 src1_sel:DWORD
	v_and_b32_sdwa v14, v9, v158 dst_sel:DWORD dst_unused:UNUSED_PAD src0_sel:WORD_1 src1_sel:DWORD
	v_and_b32_sdwa v16, v7, v158 dst_sel:DWORD dst_unused:UNUSED_PAD src0_sel:WORD_1 src1_sel:DWORD
	v_and_b32_sdwa v18, v3, v158 dst_sel:DWORD dst_unused:UNUSED_PAD src0_sel:WORD_1 src1_sel:DWORD
	v_add3_u32 v4, v4, v13, s39
	v_add3_u32 v8, v8, v15, s39
	v_add3_u32 v6, v6, v17, s39
	v_add3_u32 v2, v2, v19, s39
	v_add3_u32 v5, v5, v12, s39
	v_add3_u32 v9, v9, v14, s39
	v_add3_u32 v7, v7, v16, s39
	v_add3_u32 v12, v3, v18, s39
	v_lshrrev_b32_e32 v3, 16, v4
	v_lshrrev_b32_e32 v4, 16, v8
	v_lshrrev_b32_e32 v6, 16, v6
	v_lshrrev_b32_e32 v8, 16, v2
	v_and_or_b32 v2, v5, s35, v3
	v_and_or_b32 v4, v9, s35, v4
	v_and_or_b32 v3, v7, s35, v6
	v_and_or_b32 v5, v12, s35, v8
	v_permlane32_swap_b32_e32 v2, v4
	s_nop 0
	v_permlane32_swap_b32_e32 v3, v5
	global_store_dwordx4 v[10:11], v[2:5], off offset:224
	s_branch .LBB0_972
